# DMA-before-ds_read reorder also in P5/P8 K-loops
# speedup vs baseline: 1.0786x; 1.0014x over previous
; #define PG8_STAGE(bufoff, gbase, voff) do { _Pragma("unroll") for (int _i = 0; _i < 2; ++_i) \
;         __builtin_amdgcn_global_load_lds((const unsigned*)((const char*)(gbase) + (voff)[_i]), (PG8_LAS unsigned*)(lds + (bufoff) + ldsw + _i * 8192), 16, 0, 0); } while (0)
; #define PG8_LDA(dst, b, h) do { _Pragma("unroll") for (int m = 0; m < 4; ++m) _Pragma("unroll") for (int k = 0; k < 2; ++k) dst[m][k] = *(const PG8_LAS bf16x8*)(lds + PG8_SA(b, h) + aoff + m * 2048 + k * 1024); } while (0)
; #define PG8_LDB(dst, b, h) do { _Pragma("unroll") for (int n = 0; n < 2; ++n) _Pragma("unroll") for (int k = 0; k < 2; ++k) dst[n][k] = *(const PG8_LAS bf16x8*)(lds + PG8_SB(b, h) + boff + n * 2048 + k * 1024); } while (0)
; #define PG8_MMA(ai, bj, At, Bt) do { __builtin_amdgcn_s_setprio(1); _Pragma("unroll") for (int m = 0; m < 4; ++m) _Pragma("unroll") for (int n = 0; n < 2; ++n) _Pragma("unroll") for (int k = 0; k < 2; ++k) \
;         acc[ai][bj][m][n] = __builtin_amdgcn_mfma_f32_16x16x32_bf16(Bt[n][k], At[m][k], acc[ai][bj][m][n], 0, 0, 0); __builtin_amdgcn_s_setprio(0); } while (0)
; #define PG8_WAIT_V(n) asm volatile("s_waitcnt vmcnt(" #n ")" ::: "memory")
; #define PG8_WAIT_L(n) asm volatile("s_waitcnt lgkmcnt(" #n ")" ::: "memory")
; #define PG8_BAR __builtin_amdgcn_s_barrier()
; #define PG8_SCHED __builtin_amdgcn_sched_barrier(0)
; template <class Epi, class Sched, bool ALIGN_EPI = false, bool SP2 = false>
; __device__ __forceinline__ void gemm_phase(PG8_LAS unsigned char* lds, const Gemm g, const Sched& S, const Epi& E) {
;     ...
;             PG8_LDB(B0, 0, 0); PG8_LDB(B1, 0, 1); PG8_SCHED; PG8_LDA(At, 0, 0); PG8_STAGE(PG8_SA(1, 1), a1 + hstepA, voffA);
;             PG8_WAIT_V(8); PG8_WAIT_L(0); PG8_BAR; PG8_MMA(0, 0, At, B0); PG8_MMA(0, 1, At, B1); PG8_BAR; PG8_SCHED;
;             PG8_LDA(At, 0, 1); PG8_STAGE(PG8_SB(0, 0), b2, voffB); PG8_STAGE(PG8_SB(0, 1), b2 + hstepB, voffB); PG8_STAGE(PG8_SA(0, 0), a2, voffA);
;             PG8_WAIT_V(8); PG8_WAIT_L(0); PG8_BAR; PG8_MMA(1, 0, At, B0); PG8_MMA(1, 1, At, B1); PG8_BAR; PG8_SCHED;
.LBB0_482:
	s_add_u32 s33, s50, 0xfffc0080
	s_addc_u32 s52, s51, -1
	s_cmp_eq_u32 s74, 12
	s_cselect_b32 s55, s43, s52
	s_cselect_b32 s54, s82, s33
	s_cselect_b32 s53, s41, s85
	s_cselect_b32 s52, s83, s84
	v_lshl_add_u64 v[164:165], s[50:51], 0, v[152:153]
	s_add_i32 m0, s30, 0xc000
	global_load_lds_dwordx4 v[164:165], off
	v_lshl_add_u64 v[164:165], s[50:51], 0, v[154:155]
	s_add_i32 m0, s30, 0xe000
	s_nop 0
	global_load_lds_dwordx4 v[164:165], off
	ds_read_b128 v[128:131], v169
	ds_read_b128 v[132:135], v169 offset:1024
	ds_read_b128 v[136:139], v169 offset:2048
	ds_read_b128 v[140:143], v169 offset:3072
	ds_read_b128 v[160:163], v170
	ds_read_b128 v[176:179], v170 offset:1024
	ds_read_b128 v[180:183], v170 offset:2048
	ds_read_b128 v[184:187], v170 offset:3072
	ds_read_b128 v[188:191], v171
	ds_read_b128 v[192:195], v171 offset:1024
	ds_read_b128 v[196:199], v171 offset:2048
	ds_read_b128 v[200:203], v171 offset:3072
	ds_read_b128 v[204:207], v171 offset:4096
	ds_read_b128 v[208:211], v171 offset:5120
	ds_read_b128 v[212:215], v171 offset:6144
	ds_read_b128 v[216:219], v171 offset:7168
	s_waitcnt vmcnt(8)
	s_waitcnt lgkmcnt(0)
	s_barrier
	s_setprio 1
	s_waitcnt lgkmcnt(0)
	v_mfma_f32_16x16x32_bf16 v[124:127], v[128:131], v[188:191], v[124:127]
	v_mfma_f32_16x16x32_bf16 v[120:123], v[136:139], v[188:191], v[120:123]
	v_mfma_f32_16x16x32_bf16 v[116:119], v[128:131], v[196:199], v[116:119]
	v_mfma_f32_16x16x32_bf16 v[112:115], v[136:139], v[196:199], v[112:115]
	v_mfma_f32_16x16x32_bf16 v[108:111], v[128:131], v[204:207], v[108:111]
	v_mfma_f32_16x16x32_bf16 v[104:107], v[136:139], v[204:207], v[104:107]
	v_mfma_f32_16x16x32_bf16 v[100:103], v[128:131], v[212:215], v[100:103]
	v_mfma_f32_16x16x32_bf16 v[96:99], v[136:139], v[212:215], v[96:99]
	v_mfma_f32_16x16x32_bf16 v[124:127], v[132:135], v[192:195], v[124:127]
	v_mfma_f32_16x16x32_bf16 v[120:123], v[140:143], v[192:195], v[120:123]
	v_mfma_f32_16x16x32_bf16 v[116:119], v[132:135], v[200:203], v[116:119]
	v_mfma_f32_16x16x32_bf16 v[112:115], v[140:143], v[200:203], v[112:115]
	v_mfma_f32_16x16x32_bf16 v[108:111], v[132:135], v[208:211], v[108:111]
	v_mfma_f32_16x16x32_bf16 v[104:107], v[140:143], v[208:211], v[104:107]
	v_mfma_f32_16x16x32_bf16 v[100:103], v[132:135], v[216:219], v[100:103]
	v_mfma_f32_16x16x32_bf16 v[96:99], v[140:143], v[216:219], v[96:99]
	s_setprio 0
	s_setprio 1
	v_mfma_f32_16x16x32_bf16 v[68:71], v[160:163], v[188:191], v[68:71]
	v_mfma_f32_16x16x32_bf16 v[64:67], v[180:183], v[188:191], v[64:67]
	v_mfma_f32_16x16x32_bf16 v[52:55], v[160:163], v[196:199], v[52:55]
	v_mfma_f32_16x16x32_bf16 v[48:51], v[180:183], v[196:199], v[48:51]
	v_mfma_f32_16x16x32_bf16 v[44:47], v[160:163], v[204:207], v[44:47]
	v_mfma_f32_16x16x32_bf16 v[40:43], v[180:183], v[204:207], v[40:43]
	v_mfma_f32_16x16x32_bf16 v[36:39], v[160:163], v[212:215], v[36:39]
	v_mfma_f32_16x16x32_bf16 v[32:35], v[180:183], v[212:215], v[32:35]
	v_mfma_f32_16x16x32_bf16 v[68:71], v[176:179], v[192:195], v[68:71]
	v_mfma_f32_16x16x32_bf16 v[64:67], v[184:187], v[192:195], v[64:67]
	v_mfma_f32_16x16x32_bf16 v[52:55], v[176:179], v[200:203], v[52:55]
	v_mfma_f32_16x16x32_bf16 v[48:51], v[184:187], v[200:203], v[48:51]
	v_mfma_f32_16x16x32_bf16 v[44:47], v[176:179], v[208:211], v[44:47]
	v_mfma_f32_16x16x32_bf16 v[40:43], v[184:187], v[208:211], v[40:43]
	v_mfma_f32_16x16x32_bf16 v[36:39], v[176:179], v[216:219], v[36:39]
	v_mfma_f32_16x16x32_bf16 v[32:35], v[184:187], v[216:219], v[32:35]
	s_setprio 0
	s_barrier
	s_add_i32 s33, s61, s23
	v_lshl_add_u64 v[164:165], s[52:53], 0, v[146:147]
	s_mov_b32 m0, s33
	global_load_lds_dwordx4 v[164:165], off
	s_add_i32 m0, s33, 0x2000
	s_add_u32 s76, s52, 0x40000
	v_lshl_add_u64 v[172:173], s[52:53], 0, v[150:151]
	s_addc_u32 s77, s53, 0
	s_add_i32 s33, s66, s23
	global_load_lds_dwordx4 v[172:173], off
	v_lshl_add_u64 v[220:221], s[76:77], 0, v[146:147]
	s_mov_b32 m0, s33
	v_lshl_add_u64 v[222:223], s[54:55], 0, v[148:149]
	global_load_lds_dwordx4 v[220:221], off
	v_lshl_add_u64 v[220:221], s[76:77], 0, v[150:151]
	s_add_i32 m0, s33, 0x2000
	s_nop 0
	global_load_lds_dwordx4 v[220:221], off
	v_lshl_add_u64 v[220:221], s[54:55], 0, v[144:145]
	s_mov_b32 m0, s30
	s_nop 0
	global_load_lds_dwordx4 v[220:221], off
	s_mov_b32 m0, s31
	s_nop 0
	global_load_lds_dwordx4 v[222:223], off
	ds_read_b128 v[188:191], v171 offset:16384
	ds_read_b128 v[192:195], v171 offset:17408
	ds_read_b128 v[196:199], v171 offset:18432
	ds_read_b128 v[200:203], v171 offset:19456
	ds_read_b128 v[204:207], v171 offset:20480
	ds_read_b128 v[208:211], v171 offset:21504
	ds_read_b128 v[212:215], v171 offset:22528
	ds_read_b128 v[216:219], v171 offset:23552
	s_waitcnt vmcnt(8)
	s_waitcnt lgkmcnt(0)
	s_barrier
; #define PG8_STAGE(bufoff, gbase, voff) do { _Pragma("unroll") for (int _i = 0; _i < 2; ++_i) \
;         __builtin_amdgcn_global_load_lds((const unsigned*)((const char*)(gbase) + (voff)[_i]), (PG8_LAS unsigned*)(lds + (bufoff) + ldsw + _i * 8192), 16, 0, 0); } while (0)
; #define PG8_LDA(dst, b, h) do { _Pragma("unroll") for (int m = 0; m < 4; ++m) _Pragma("unroll") for (int k = 0; k < 2; ++k) dst[m][k] = *(const PG8_LAS bf16x8*)(lds + PG8_SA(b, h) + aoff + m * 2048 + k * 1024); } while (0)
; #define PG8_LDB(dst, b, h) do { _Pragma("unroll") for (int n = 0; n < 2; ++n) _Pragma("unroll") for (int k = 0; k < 2; ++k) dst[n][k] = *(const PG8_LAS bf16x8*)(lds + PG8_SB(b, h) + boff + n * 2048 + k * 1024); } while (0)
; #define PG8_MMA(ai, bj, At, Bt) do { __builtin_amdgcn_s_setprio(1); _Pragma("unroll") for (int m = 0; m < 4; ++m) _Pragma("unroll") for (int n = 0; n < 2; ++n) _Pragma("unroll") for (int k = 0; k < 2; ++k) \
;         acc[ai][bj][m][n] = __builtin_amdgcn_mfma_f32_16x16x32_bf16(Bt[n][k], At[m][k], acc[ai][bj][m][n], 0, 0, 0); __builtin_amdgcn_s_setprio(0); } while (0)
; #define PG8_WAIT_V(n) asm volatile("s_waitcnt vmcnt(" #n ")" ::: "memory")
; #define PG8_WAIT_L(n) asm volatile("s_waitcnt lgkmcnt(" #n ")" ::: "memory")
; #define PG8_BAR __builtin_amdgcn_s_barrier()
; #define PG8_SCHED __builtin_amdgcn_sched_barrier(0)
; template <class Epi, class Sched, bool ALIGN_EPI = false, bool SP2 = false>
; __device__ __forceinline__ void gemm_phase(PG8_LAS unsigned char* lds, const Gemm g, const Sched& S, const Epi& E) {
;     ...
;             PG8_WAIT_V(8); PG8_WAIT_L(0); PG8_BAR; PG8_MMA(1, 0, At, B0); PG8_MMA(1, 1, At, B1); PG8_BAR; PG8_SCHED;
;             PG8_LDB(B0, 1, 0); PG8_LDB(B1, 1, 1); PG8_SCHED; PG8_LDA(At, 1, 0); PG8_STAGE(PG8_SA(0, 1), a2 + hstepA, voffA);
;             PG8_WAIT_V(8); PG8_WAIT_L(0); PG8_BAR; PG8_MMA(0, 0, At, B0); PG8_MMA(0, 1, At, B1); PG8_BAR; PG8_SCHED;
	s_setprio 1
	s_waitcnt lgkmcnt(0)
	v_mfma_f32_16x16x32_bf16 v[92:95], v[128:131], v[188:191], v[92:95]
	v_mfma_f32_16x16x32_bf16 v[88:91], v[136:139], v[188:191], v[88:91]
	v_mfma_f32_16x16x32_bf16 v[84:87], v[128:131], v[196:199], v[84:87]
	v_mfma_f32_16x16x32_bf16 v[80:83], v[136:139], v[196:199], v[80:83]
	v_mfma_f32_16x16x32_bf16 v[76:79], v[128:131], v[204:207], v[76:79]
	v_mfma_f32_16x16x32_bf16 v[72:75], v[136:139], v[204:207], v[72:75]
	v_mfma_f32_16x16x32_bf16 v[60:63], v[128:131], v[212:215], v[60:63]
	v_mfma_f32_16x16x32_bf16 v[56:59], v[136:139], v[212:215], v[56:59]
	v_mfma_f32_16x16x32_bf16 v[92:95], v[132:135], v[192:195], v[92:95]
	v_mfma_f32_16x16x32_bf16 v[88:91], v[140:143], v[192:195], v[88:91]
	v_mfma_f32_16x16x32_bf16 v[84:87], v[132:135], v[200:203], v[84:87]
	v_mfma_f32_16x16x32_bf16 v[80:83], v[140:143], v[200:203], v[80:83]
	v_mfma_f32_16x16x32_bf16 v[76:79], v[132:135], v[208:211], v[76:79]
	v_mfma_f32_16x16x32_bf16 v[72:75], v[140:143], v[208:211], v[72:75]
	v_mfma_f32_16x16x32_bf16 v[60:63], v[132:135], v[216:219], v[60:63]
	v_mfma_f32_16x16x32_bf16 v[56:59], v[140:143], v[216:219], v[56:59]
	s_setprio 0
	s_setprio 1
	v_mfma_f32_16x16x32_bf16 v[28:31], v[160:163], v[188:191], v[28:31]
	v_mfma_f32_16x16x32_bf16 v[24:27], v[180:183], v[188:191], v[24:27]
	v_mfma_f32_16x16x32_bf16 v[20:23], v[160:163], v[196:199], v[20:23]
	v_mfma_f32_16x16x32_bf16 v[16:19], v[180:183], v[196:199], v[16:19]
	v_mfma_f32_16x16x32_bf16 v[12:15], v[160:163], v[204:207], v[12:15]
	v_mfma_f32_16x16x32_bf16 v[8:11], v[180:183], v[204:207], v[8:11]
	v_mfma_f32_16x16x32_bf16 v[4:7], v[160:163], v[212:215], v[4:7]
	v_mfma_f32_16x16x32_bf16 v[0:3], v[180:183], v[212:215], v[0:3]
	v_mfma_f32_16x16x32_bf16 v[28:31], v[176:179], v[192:195], v[28:31]
	v_mfma_f32_16x16x32_bf16 v[24:27], v[184:187], v[192:195], v[24:27]
	v_mfma_f32_16x16x32_bf16 v[20:23], v[176:179], v[200:203], v[20:23]
	v_mfma_f32_16x16x32_bf16 v[16:19], v[184:187], v[200:203], v[16:19]
	v_mfma_f32_16x16x32_bf16 v[12:15], v[176:179], v[208:211], v[12:15]
	v_mfma_f32_16x16x32_bf16 v[8:11], v[184:187], v[208:211], v[8:11]
	v_mfma_f32_16x16x32_bf16 v[4:7], v[176:179], v[216:219], v[4:7]
	v_mfma_f32_16x16x32_bf16 v[0:3], v[184:187], v[216:219], v[0:3]
	s_setprio 0
	s_barrier
	s_add_i32 s33, 0, 0x18000
	s_add_i32 s75, 0, 0x1c000
	v_add_u32_e32 v140, s33, v167
	v_add_u32_e32 v175, s75, v167
	s_add_u32 s54, s54, 0x40000
	s_addc_u32 s55, s55, 0
	s_mov_b32 m0, s35
	v_lshl_add_u64 v[224:225], s[54:55], 0, v[144:145]
	global_load_lds_dwordx4 v[224:225], off
	v_lshl_add_u64 v[224:225], s[54:55], 0, v[148:149]
	s_mov_b32 m0, s38
	s_nop 0
	global_load_lds_dwordx4 v[224:225], off
	ds_read_b128 v[128:131], v140
	ds_read_b128 v[132:135], v140 offset:1024
	ds_read_b128 v[136:139], v140 offset:2048
	ds_read_b128 v[140:143], v140 offset:3072
	ds_read_b128 v[160:163], v175
	ds_read_b128 v[176:179], v175 offset:1024
	ds_read_b128 v[180:183], v175 offset:2048
	ds_read_b128 v[184:187], v175 offset:3072
	ds_read_b128 v[188:191], v171 offset:32768
	ds_read_b128 v[192:195], v171 offset:33792
	ds_read_b128 v[196:199], v171 offset:34816
	ds_read_b128 v[200:203], v171 offset:35840
	ds_read_b128 v[204:207], v171 offset:36864
	ds_read_b128 v[208:211], v171 offset:37888
	ds_read_b128 v[212:215], v171 offset:38912
	ds_read_b128 v[216:219], v171 offset:39936
	s_waitcnt vmcnt(8)
	s_waitcnt lgkmcnt(0)
	s_barrier
	s_setprio 1
	s_waitcnt lgkmcnt(0)
	v_mfma_f32_16x16x32_bf16 v[124:127], v[128:131], v[188:191], v[124:127]
	v_mfma_f32_16x16x32_bf16 v[120:123], v[136:139], v[188:191], v[120:123]
	v_mfma_f32_16x16x32_bf16 v[116:119], v[128:131], v[196:199], v[116:119]
	v_mfma_f32_16x16x32_bf16 v[112:115], v[136:139], v[196:199], v[112:115]
	v_mfma_f32_16x16x32_bf16 v[108:111], v[128:131], v[204:207], v[108:111]
	v_mfma_f32_16x16x32_bf16 v[104:107], v[136:139], v[204:207], v[104:107]
	v_mfma_f32_16x16x32_bf16 v[100:103], v[128:131], v[212:215], v[100:103]
	v_mfma_f32_16x16x32_bf16 v[96:99], v[136:139], v[212:215], v[96:99]
	v_mfma_f32_16x16x32_bf16 v[124:127], v[132:135], v[192:195], v[124:127]
	v_mfma_f32_16x16x32_bf16 v[120:123], v[140:143], v[192:195], v[120:123]
	v_mfma_f32_16x16x32_bf16 v[116:119], v[132:135], v[200:203], v[116:119]
	v_mfma_f32_16x16x32_bf16 v[112:115], v[140:143], v[200:203], v[112:115]
	v_mfma_f32_16x16x32_bf16 v[108:111], v[132:135], v[208:211], v[108:111]
	v_mfma_f32_16x16x32_bf16 v[104:107], v[140:143], v[208:211], v[104:107]
	v_mfma_f32_16x16x32_bf16 v[100:103], v[132:135], v[216:219], v[100:103]
	v_mfma_f32_16x16x32_bf16 v[96:99], v[140:143], v[216:219], v[96:99]
	s_setprio 0
	s_setprio 1
	v_mfma_f32_16x16x32_bf16 v[68:71], v[160:163], v[188:191], v[68:71]
	v_mfma_f32_16x16x32_bf16 v[64:67], v[180:183], v[188:191], v[64:67]
	v_mfma_f32_16x16x32_bf16 v[52:55], v[160:163], v[196:199], v[52:55]
	v_mfma_f32_16x16x32_bf16 v[48:51], v[180:183], v[196:199], v[48:51]
	v_mfma_f32_16x16x32_bf16 v[44:47], v[160:163], v[204:207], v[44:47]
	v_mfma_f32_16x16x32_bf16 v[40:43], v[180:183], v[204:207], v[40:43]
	v_mfma_f32_16x16x32_bf16 v[36:39], v[160:163], v[212:215], v[36:39]
	v_mfma_f32_16x16x32_bf16 v[32:35], v[180:183], v[212:215], v[32:35]
	v_mfma_f32_16x16x32_bf16 v[68:71], v[176:179], v[192:195], v[68:71]
	v_mfma_f32_16x16x32_bf16 v[64:67], v[184:187], v[192:195], v[64:67]
	v_mfma_f32_16x16x32_bf16 v[52:55], v[176:179], v[200:203], v[52:55]
	v_mfma_f32_16x16x32_bf16 v[48:51], v[184:187], v[200:203], v[48:51]
	v_mfma_f32_16x16x32_bf16 v[44:47], v[176:179], v[208:211], v[44:47]
	v_mfma_f32_16x16x32_bf16 v[40:43], v[184:187], v[208:211], v[40:43]
	v_mfma_f32_16x16x32_bf16 v[36:39], v[176:179], v[216:219], v[36:39]
	v_mfma_f32_16x16x32_bf16 v[32:35], v[184:187], v[216:219], v[32:35]
	s_setprio 0
	s_barrier
; #define PG8_STAGE(bufoff, gbase, voff) do { _Pragma("unroll") for (int _i = 0; _i < 2; ++_i) \
;         __builtin_amdgcn_global_load_lds((const unsigned*)((const char*)(gbase) + (voff)[_i]), (PG8_LAS unsigned*)(lds + (bufoff) + ldsw + _i * 8192), 16, 0, 0); } while (0)
; #define PG8_LDA(dst, b, h) do { _Pragma("unroll") for (int m = 0; m < 4; ++m) _Pragma("unroll") for (int k = 0; k < 2; ++k) dst[m][k] = *(const PG8_LAS bf16x8*)(lds + PG8_SA(b, h) + aoff + m * 2048 + k * 1024); } while (0)
; #define PG8_MMA(ai, bj, At, Bt) do { __builtin_amdgcn_s_setprio(1); _Pragma("unroll") for (int m = 0; m < 4; ++m) _Pragma("unroll") for (int n = 0; n < 2; ++n) _Pragma("unroll") for (int k = 0; k < 2; ++k) \
;         acc[ai][bj][m][n] = __builtin_amdgcn_mfma_f32_16x16x32_bf16(Bt[n][k], At[m][k], acc[ai][bj][m][n], 0, 0, 0); __builtin_amdgcn_s_setprio(0); } while (0)
; #define PG8_WAIT_V(n) asm volatile("s_waitcnt vmcnt(" #n ")" ::: "memory")
; #define PG8_WAIT_L(n) asm volatile("s_waitcnt lgkmcnt(" #n ")" ::: "memory")
; #define PG8_BAR __builtin_amdgcn_s_barrier()
; #define PG8_SCHED __builtin_amdgcn_sched_barrier(0)
; template <class Epi, class Sched, bool ALIGN_EPI = false, bool SP2 = false>
; __device__ __forceinline__ void gemm_phase(PG8_LAS unsigned char* lds, const Gemm g, const Sched& S, const Epi& E) {
;     ...
;             PG8_LDA(At, 1, 1); PG8_STAGE(PG8_SB(1, 0), b3, voffB); PG8_STAGE(PG8_SB(1, 1), b3 + hstepB, voffB); PG8_STAGE(PG8_SA(1, 0), a3, voffA);
;             PG8_WAIT_V(8); PG8_WAIT_L(0); PG8_BAR; PG8_MMA(1, 0, At, B0); PG8_MMA(1, 1, At, B1); PG8_BAR; PG8_SCHED;
;     ...
;         if constexpr (ALIGN_EPI) { if (wr == 0) PG8_BAR; }
	s_add_i32 s33, s33, s23
	v_lshl_add_u64 v[164:165], v[164:165], 0, s[8:9]
	s_mov_b32 m0, s33
	global_load_lds_dwordx4 v[164:165], off
	s_add_i32 m0, s33, 0x2000
	s_add_u32 s52, s52, 0x40080
	v_lshl_add_u64 v[164:165], v[172:173], 0, s[8:9]
	s_addc_u32 s53, s53, 0
	s_add_i32 s33, s75, s23
	global_load_lds_dwordx4 v[164:165], off
	v_lshl_add_u64 v[164:165], s[52:53], 0, v[146:147]
	s_mov_b32 m0, s33
	s_nop 0
	global_load_lds_dwordx4 v[164:165], off
	v_lshl_add_u64 v[164:165], s[52:53], 0, v[150:151]
	s_add_i32 m0, s33, 0x2000
	s_nop 0
	global_load_lds_dwordx4 v[164:165], off
	v_lshl_add_u64 v[164:165], v[220:221], 0, s[8:9]
	s_mov_b32 m0, s57
	s_nop 0
	global_load_lds_dwordx4 v[164:165], off
	v_lshl_add_u64 v[164:165], v[222:223], 0, s[8:9]
	s_mov_b32 m0, s58
	s_nop 0
	global_load_lds_dwordx4 v[164:165], off
	ds_read_b128 v[188:191], v171 offset:49152
	ds_read_b128 v[192:195], v171 offset:50176
	ds_read_b128 v[196:199], v171 offset:51200
	ds_read_b128 v[200:203], v171 offset:52224
	ds_read_b128 v[204:207], v171 offset:53248
	ds_read_b128 v[208:211], v171 offset:54272
	ds_read_b128 v[212:215], v171 offset:55296
	ds_read_b128 v[216:219], v171 offset:56320
	s_waitcnt vmcnt(8)
	s_waitcnt lgkmcnt(0)
	s_barrier
	s_setprio 1
	s_waitcnt lgkmcnt(0)
	v_mfma_f32_16x16x32_bf16 v[92:95], v[128:131], v[188:191], v[92:95]
	v_mfma_f32_16x16x32_bf16 v[88:91], v[136:139], v[188:191], v[88:91]
	v_mfma_f32_16x16x32_bf16 v[84:87], v[128:131], v[196:199], v[84:87]
	v_mfma_f32_16x16x32_bf16 v[80:83], v[136:139], v[196:199], v[80:83]
	v_mfma_f32_16x16x32_bf16 v[76:79], v[128:131], v[204:207], v[76:79]
	v_mfma_f32_16x16x32_bf16 v[72:75], v[136:139], v[204:207], v[72:75]
	v_mfma_f32_16x16x32_bf16 v[60:63], v[128:131], v[212:215], v[60:63]
	v_mfma_f32_16x16x32_bf16 v[56:59], v[136:139], v[212:215], v[56:59]
	v_mfma_f32_16x16x32_bf16 v[92:95], v[132:135], v[192:195], v[92:95]
	v_mfma_f32_16x16x32_bf16 v[88:91], v[140:143], v[192:195], v[88:91]
	v_mfma_f32_16x16x32_bf16 v[84:87], v[132:135], v[200:203], v[84:87]
	v_mfma_f32_16x16x32_bf16 v[80:83], v[140:143], v[200:203], v[80:83]
	v_mfma_f32_16x16x32_bf16 v[76:79], v[132:135], v[208:211], v[76:79]
	v_mfma_f32_16x16x32_bf16 v[72:75], v[140:143], v[208:211], v[72:75]
	v_mfma_f32_16x16x32_bf16 v[60:63], v[132:135], v[216:219], v[60:63]
	v_mfma_f32_16x16x32_bf16 v[56:59], v[140:143], v[216:219], v[56:59]
	s_setprio 0
	s_setprio 1
	v_mfma_f32_16x16x32_bf16 v[28:31], v[160:163], v[188:191], v[28:31]
	v_mfma_f32_16x16x32_bf16 v[24:27], v[180:183], v[188:191], v[24:27]
	v_mfma_f32_16x16x32_bf16 v[20:23], v[160:163], v[196:199], v[20:23]
	v_mfma_f32_16x16x32_bf16 v[16:19], v[180:183], v[196:199], v[16:19]
	v_mfma_f32_16x16x32_bf16 v[12:15], v[160:163], v[204:207], v[12:15]
	v_mfma_f32_16x16x32_bf16 v[8:11], v[180:183], v[204:207], v[8:11]
	v_mfma_f32_16x16x32_bf16 v[4:7], v[160:163], v[212:215], v[4:7]
	v_mfma_f32_16x16x32_bf16 v[0:3], v[180:183], v[212:215], v[0:3]
	v_mfma_f32_16x16x32_bf16 v[28:31], v[176:179], v[192:195], v[28:31]
	v_mfma_f32_16x16x32_bf16 v[24:27], v[184:187], v[192:195], v[24:27]
	v_mfma_f32_16x16x32_bf16 v[20:23], v[176:179], v[200:203], v[20:23]
	v_mfma_f32_16x16x32_bf16 v[16:19], v[184:187], v[200:203], v[16:19]
	v_mfma_f32_16x16x32_bf16 v[12:15], v[176:179], v[208:211], v[12:15]
	v_mfma_f32_16x16x32_bf16 v[8:11], v[184:187], v[208:211], v[8:11]
	v_mfma_f32_16x16x32_bf16 v[4:7], v[176:179], v[216:219], v[4:7]
	v_mfma_f32_16x16x32_bf16 v[0:3], v[184:187], v[216:219], v[0:3]
	s_setprio 0
	s_barrier
	s_add_i32 s74, s74, 2
	s_add_u32 s50, s50, 0x100
	s_addc_u32 s51, s51, 0
	s_add_u32 s84, s84, 0x100
	s_addc_u32 s85, s85, 0
	s_cmp_gt_u32 s74, 13
	s_cbranch_scc0 .LBB0_482
	s_and_b64 vcc, exec, s[10:11]
	s_cbranch_vccz .LBB0_485
	s_barrier

; #define PG8_STAGE(bufoff, gbase, voff) do { _Pragma("unroll") for (int _i = 0; _i < 2; ++_i) \
;         __builtin_amdgcn_global_load_lds((const unsigned*)((const char*)(gbase) + (voff)[_i]), (PG8_LAS unsigned*)(lds + (bufoff) + ldsw + _i * 8192), 16, 0, 0); } while (0)
; #define PG8_LDA(dst, b, h) do { _Pragma("unroll") for (int m = 0; m < 4; ++m) _Pragma("unroll") for (int k = 0; k < 2; ++k) dst[m][k] = *(const PG8_LAS bf16x8*)(lds + PG8_SA(b, h) + aoff + m * 2048 + k * 1024); } while (0)
; #define PG8_LDB(dst, b, h) do { _Pragma("unroll") for (int n = 0; n < 2; ++n) _Pragma("unroll") for (int k = 0; k < 2; ++k) dst[n][k] = *(const PG8_LAS bf16x8*)(lds + PG8_SB(b, h) + boff + n * 2048 + k * 1024); } while (0)
; #define PG8_MMA(ai, bj, At, Bt) do { __builtin_amdgcn_s_setprio(1); _Pragma("unroll") for (int m = 0; m < 4; ++m) _Pragma("unroll") for (int n = 0; n < 2; ++n) _Pragma("unroll") for (int k = 0; k < 2; ++k) \
;         acc[ai][bj][m][n] = __builtin_amdgcn_mfma_f32_16x16x32_bf16(Bt[n][k], At[m][k], acc[ai][bj][m][n], 0, 0, 0); __builtin_amdgcn_s_setprio(0); } while (0)
; #define PG8_WAIT_V(n) asm volatile("s_waitcnt vmcnt(" #n ")" ::: "memory")
; #define PG8_WAIT_L(n) asm volatile("s_waitcnt lgkmcnt(" #n ")" ::: "memory")
; #define PG8_BAR __builtin_amdgcn_s_barrier()
; #define PG8_SCHED __builtin_amdgcn_sched_barrier(0)
; template <class Epi, class Sched, bool ALIGN_EPI = false, bool SP2 = false>
; __device__ __forceinline__ void gemm_phase(PG8_LAS unsigned char* lds, const Gemm g, const Sched& S, const Epi& E) {
;     ...
;             PG8_LDB(B0, 0, 0); PG8_LDB(B1, 0, 1); PG8_SCHED; PG8_LDA(At, 0, 0); PG8_STAGE(PG8_SA(1, 1), a1 + hstepA, voffA);
;             PG8_WAIT_V(8); PG8_WAIT_L(0); PG8_BAR; PG8_MMA(0, 0, At, B0); PG8_MMA(0, 1, At, B1); PG8_BAR; PG8_SCHED;
;             PG8_LDA(At, 0, 1); PG8_STAGE(PG8_SB(0, 0), b2, voffB); PG8_STAGE(PG8_SB(0, 1), b2 + hstepB, voffB); PG8_STAGE(PG8_SA(0, 0), a2, voffA);
;             PG8_WAIT_V(8); PG8_WAIT_L(0); PG8_BAR; PG8_MMA(1, 0, At, B0); PG8_MMA(1, 1, At, B1); PG8_BAR; PG8_SCHED;
.LBB0_685:
	s_add_u32 s38, s36, 0x100
	s_addc_u32 s39, s37, 0
	s_cmp_eq_u32 s62, 40
	s_cselect_b32 s43, s5, s39
	s_cselect_b32 s42, s4, s38
	s_cselect_b32 s41, s25, s61
	s_cselect_b32 s40, s24, s60
	v_lshl_add_u64 v[164:165], s[36:37], 0, v[152:153]
	s_add_i32 m0, s28, 0xc000
	global_load_lds_dwordx4 v[164:165], off
	v_lshl_add_u64 v[164:165], s[36:37], 0, v[154:155]
	s_add_i32 m0, s28, 0xe000
	s_nop 0
	global_load_lds_dwordx4 v[164:165], off
	ds_read_b128 v[128:131], v169
	ds_read_b128 v[132:135], v169 offset:1024
	ds_read_b128 v[136:139], v169 offset:2048
	ds_read_b128 v[140:143], v169 offset:3072
	ds_read_b128 v[160:163], v170
	ds_read_b128 v[176:179], v170 offset:1024
	ds_read_b128 v[180:183], v170 offset:2048
	ds_read_b128 v[184:187], v170 offset:3072
	ds_read_b128 v[188:191], v171
	ds_read_b128 v[192:195], v171 offset:1024
	ds_read_b128 v[196:199], v171 offset:2048
	ds_read_b128 v[200:203], v171 offset:3072
	ds_read_b128 v[204:207], v171 offset:4096
	ds_read_b128 v[208:211], v171 offset:5120
	ds_read_b128 v[212:215], v171 offset:6144
	ds_read_b128 v[216:219], v171 offset:7168
	s_waitcnt vmcnt(8)
	s_waitcnt lgkmcnt(0)
	s_barrier
	s_setprio 1
	s_waitcnt lgkmcnt(0)
	v_mfma_f32_16x16x32_bf16 v[124:127], v[128:131], v[188:191], v[124:127]
	v_mfma_f32_16x16x32_bf16 v[120:123], v[136:139], v[188:191], v[120:123]
	v_mfma_f32_16x16x32_bf16 v[116:119], v[128:131], v[196:199], v[116:119]
	v_mfma_f32_16x16x32_bf16 v[112:115], v[136:139], v[196:199], v[112:115]
	v_mfma_f32_16x16x32_bf16 v[108:111], v[128:131], v[204:207], v[108:111]
	v_mfma_f32_16x16x32_bf16 v[104:107], v[136:139], v[204:207], v[104:107]
	v_mfma_f32_16x16x32_bf16 v[100:103], v[128:131], v[212:215], v[100:103]
	v_mfma_f32_16x16x32_bf16 v[96:99], v[136:139], v[212:215], v[96:99]
	v_mfma_f32_16x16x32_bf16 v[124:127], v[132:135], v[192:195], v[124:127]
	v_mfma_f32_16x16x32_bf16 v[120:123], v[140:143], v[192:195], v[120:123]
	v_mfma_f32_16x16x32_bf16 v[116:119], v[132:135], v[200:203], v[116:119]
	v_mfma_f32_16x16x32_bf16 v[112:115], v[140:143], v[200:203], v[112:115]
	v_mfma_f32_16x16x32_bf16 v[108:111], v[132:135], v[208:211], v[108:111]
	v_mfma_f32_16x16x32_bf16 v[104:107], v[140:143], v[208:211], v[104:107]
	v_mfma_f32_16x16x32_bf16 v[100:103], v[132:135], v[216:219], v[100:103]
	v_mfma_f32_16x16x32_bf16 v[96:99], v[140:143], v[216:219], v[96:99]
	s_setprio 0
	s_setprio 1
	v_mfma_f32_16x16x32_bf16 v[68:71], v[160:163], v[188:191], v[68:71]
	v_mfma_f32_16x16x32_bf16 v[64:67], v[180:183], v[188:191], v[64:67]
	v_mfma_f32_16x16x32_bf16 v[52:55], v[160:163], v[196:199], v[52:55]
	v_mfma_f32_16x16x32_bf16 v[48:51], v[180:183], v[196:199], v[48:51]
	v_mfma_f32_16x16x32_bf16 v[44:47], v[160:163], v[204:207], v[44:47]
	v_mfma_f32_16x16x32_bf16 v[40:43], v[180:183], v[204:207], v[40:43]
	v_mfma_f32_16x16x32_bf16 v[36:39], v[160:163], v[212:215], v[36:39]
	v_mfma_f32_16x16x32_bf16 v[32:35], v[180:183], v[212:215], v[32:35]
	v_mfma_f32_16x16x32_bf16 v[68:71], v[176:179], v[192:195], v[68:71]
	v_mfma_f32_16x16x32_bf16 v[64:67], v[184:187], v[192:195], v[64:67]
	v_mfma_f32_16x16x32_bf16 v[52:55], v[176:179], v[200:203], v[52:55]
	v_mfma_f32_16x16x32_bf16 v[48:51], v[184:187], v[200:203], v[48:51]
	v_mfma_f32_16x16x32_bf16 v[44:47], v[176:179], v[208:211], v[44:47]
	v_mfma_f32_16x16x32_bf16 v[40:43], v[184:187], v[208:211], v[40:43]
	v_mfma_f32_16x16x32_bf16 v[36:39], v[176:179], v[216:219], v[36:39]
	v_mfma_f32_16x16x32_bf16 v[32:35], v[184:187], v[216:219], v[32:35]
	s_setprio 0
	s_barrier
	s_add_i32 s33, s50, s23
	v_lshl_add_u64 v[164:165], s[40:41], 0, v[146:147]
	s_mov_b32 m0, s33
	global_load_lds_dwordx4 v[164:165], off
	s_add_i32 m0, s33, 0x2000
	s_add_u32 s36, s40, 0xb0000
	v_lshl_add_u64 v[172:173], s[40:41], 0, v[150:151]
	s_addc_u32 s37, s41, 0
	s_add_i32 s33, s51, s23
	global_load_lds_dwordx4 v[172:173], off
	v_lshl_add_u64 v[220:221], s[36:37], 0, v[146:147]
	s_mov_b32 m0, s33
	v_lshl_add_u64 v[222:223], s[42:43], 0, v[148:149]
	global_load_lds_dwordx4 v[220:221], off
	v_lshl_add_u64 v[220:221], s[36:37], 0, v[150:151]
	s_add_i32 m0, s33, 0x2000
	s_nop 0
	global_load_lds_dwordx4 v[220:221], off
	v_lshl_add_u64 v[220:221], s[42:43], 0, v[144:145]
	s_mov_b32 m0, s28
	s_nop 0
	global_load_lds_dwordx4 v[220:221], off
	s_mov_b32 m0, s29
	s_nop 0
	global_load_lds_dwordx4 v[222:223], off
	ds_read_b128 v[188:191], v171 offset:16384
	ds_read_b128 v[192:195], v171 offset:17408
	ds_read_b128 v[196:199], v171 offset:18432
	ds_read_b128 v[200:203], v171 offset:19456
	ds_read_b128 v[204:207], v171 offset:20480
	ds_read_b128 v[208:211], v171 offset:21504
	ds_read_b128 v[212:215], v171 offset:22528
	ds_read_b128 v[216:219], v171 offset:23552
	s_waitcnt vmcnt(8)
	s_waitcnt lgkmcnt(0)
	s_barrier
; #define PG8_STAGE(bufoff, gbase, voff) do { _Pragma("unroll") for (int _i = 0; _i < 2; ++_i) \
;         __builtin_amdgcn_global_load_lds((const unsigned*)((const char*)(gbase) + (voff)[_i]), (PG8_LAS unsigned*)(lds + (bufoff) + ldsw + _i * 8192), 16, 0, 0); } while (0)
; #define PG8_LDA(dst, b, h) do { _Pragma("unroll") for (int m = 0; m < 4; ++m) _Pragma("unroll") for (int k = 0; k < 2; ++k) dst[m][k] = *(const PG8_LAS bf16x8*)(lds + PG8_SA(b, h) + aoff + m * 2048 + k * 1024); } while (0)
; #define PG8_LDB(dst, b, h) do { _Pragma("unroll") for (int n = 0; n < 2; ++n) _Pragma("unroll") for (int k = 0; k < 2; ++k) dst[n][k] = *(const PG8_LAS bf16x8*)(lds + PG8_SB(b, h) + boff + n * 2048 + k * 1024); } while (0)
; #define PG8_MMA(ai, bj, At, Bt) do { __builtin_amdgcn_s_setprio(1); _Pragma("unroll") for (int m = 0; m < 4; ++m) _Pragma("unroll") for (int n = 0; n < 2; ++n) _Pragma("unroll") for (int k = 0; k < 2; ++k) \
;         acc[ai][bj][m][n] = __builtin_amdgcn_mfma_f32_16x16x32_bf16(Bt[n][k], At[m][k], acc[ai][bj][m][n], 0, 0, 0); __builtin_amdgcn_s_setprio(0); } while (0)
; #define PG8_WAIT_V(n) asm volatile("s_waitcnt vmcnt(" #n ")" ::: "memory")
; #define PG8_WAIT_L(n) asm volatile("s_waitcnt lgkmcnt(" #n ")" ::: "memory")
; #define PG8_BAR __builtin_amdgcn_s_barrier()
; #define PG8_SCHED __builtin_amdgcn_sched_barrier(0)
; template <class Epi, class Sched, bool ALIGN_EPI = false, bool SP2 = false>
; __device__ __forceinline__ void gemm_phase(PG8_LAS unsigned char* lds, const Gemm g, const Sched& S, const Epi& E) {
;     ...
;             PG8_WAIT_V(8); PG8_WAIT_L(0); PG8_BAR; PG8_MMA(1, 0, At, B0); PG8_MMA(1, 1, At, B1); PG8_BAR; PG8_SCHED;
;             PG8_LDB(B0, 1, 0); PG8_LDB(B1, 1, 1); PG8_SCHED; PG8_LDA(At, 1, 0); PG8_STAGE(PG8_SA(0, 1), a2 + hstepA, voffA);
;             PG8_WAIT_V(8); PG8_WAIT_L(0); PG8_BAR; PG8_MMA(0, 0, At, B0); PG8_MMA(0, 1, At, B1); PG8_BAR; PG8_SCHED;
	s_setprio 1
	s_waitcnt lgkmcnt(0)
	v_mfma_f32_16x16x32_bf16 v[92:95], v[128:131], v[188:191], v[92:95]
	v_mfma_f32_16x16x32_bf16 v[88:91], v[136:139], v[188:191], v[88:91]
	v_mfma_f32_16x16x32_bf16 v[84:87], v[128:131], v[196:199], v[84:87]
	v_mfma_f32_16x16x32_bf16 v[80:83], v[136:139], v[196:199], v[80:83]
	v_mfma_f32_16x16x32_bf16 v[76:79], v[128:131], v[204:207], v[76:79]
	v_mfma_f32_16x16x32_bf16 v[72:75], v[136:139], v[204:207], v[72:75]
	v_mfma_f32_16x16x32_bf16 v[60:63], v[128:131], v[212:215], v[60:63]
	v_mfma_f32_16x16x32_bf16 v[56:59], v[136:139], v[212:215], v[56:59]
	v_mfma_f32_16x16x32_bf16 v[92:95], v[132:135], v[192:195], v[92:95]
	v_mfma_f32_16x16x32_bf16 v[88:91], v[140:143], v[192:195], v[88:91]
	v_mfma_f32_16x16x32_bf16 v[84:87], v[132:135], v[200:203], v[84:87]
	v_mfma_f32_16x16x32_bf16 v[80:83], v[140:143], v[200:203], v[80:83]
	v_mfma_f32_16x16x32_bf16 v[76:79], v[132:135], v[208:211], v[76:79]
	v_mfma_f32_16x16x32_bf16 v[72:75], v[140:143], v[208:211], v[72:75]
	v_mfma_f32_16x16x32_bf16 v[60:63], v[132:135], v[216:219], v[60:63]
	v_mfma_f32_16x16x32_bf16 v[56:59], v[140:143], v[216:219], v[56:59]
	s_setprio 0
	s_setprio 1
	v_mfma_f32_16x16x32_bf16 v[28:31], v[160:163], v[188:191], v[28:31]
	v_mfma_f32_16x16x32_bf16 v[24:27], v[180:183], v[188:191], v[24:27]
	v_mfma_f32_16x16x32_bf16 v[20:23], v[160:163], v[196:199], v[20:23]
	v_mfma_f32_16x16x32_bf16 v[16:19], v[180:183], v[196:199], v[16:19]
	v_mfma_f32_16x16x32_bf16 v[12:15], v[160:163], v[204:207], v[12:15]
	v_mfma_f32_16x16x32_bf16 v[8:11], v[180:183], v[204:207], v[8:11]
	v_mfma_f32_16x16x32_bf16 v[4:7], v[160:163], v[212:215], v[4:7]
	v_mfma_f32_16x16x32_bf16 v[0:3], v[180:183], v[212:215], v[0:3]
	v_mfma_f32_16x16x32_bf16 v[28:31], v[176:179], v[192:195], v[28:31]
	v_mfma_f32_16x16x32_bf16 v[24:27], v[184:187], v[192:195], v[24:27]
	v_mfma_f32_16x16x32_bf16 v[20:23], v[176:179], v[200:203], v[20:23]
	v_mfma_f32_16x16x32_bf16 v[16:19], v[184:187], v[200:203], v[16:19]
	v_mfma_f32_16x16x32_bf16 v[12:15], v[176:179], v[208:211], v[12:15]
	v_mfma_f32_16x16x32_bf16 v[8:11], v[184:187], v[208:211], v[8:11]
	v_mfma_f32_16x16x32_bf16 v[4:7], v[176:179], v[216:219], v[4:7]
	v_mfma_f32_16x16x32_bf16 v[0:3], v[184:187], v[216:219], v[0:3]
	s_setprio 0
	s_barrier
	s_add_i32 s33, 0, 0x18000
	s_add_i32 s63, 0, 0x1c000
	v_add_u32_e32 v140, s33, v167
	v_add_u32_e32 v175, s63, v167
	s_add_u32 s36, s42, 0xb0000
	s_addc_u32 s37, s43, 0
	s_mov_b32 m0, s30
	v_lshl_add_u64 v[224:225], s[36:37], 0, v[144:145]
	global_load_lds_dwordx4 v[224:225], off
	v_lshl_add_u64 v[224:225], s[36:37], 0, v[148:149]
	s_mov_b32 m0, s31
	s_nop 0
	global_load_lds_dwordx4 v[224:225], off
	ds_read_b128 v[128:131], v140
	ds_read_b128 v[132:135], v140 offset:1024
	ds_read_b128 v[136:139], v140 offset:2048
	ds_read_b128 v[140:143], v140 offset:3072
	ds_read_b128 v[160:163], v175
	ds_read_b128 v[176:179], v175 offset:1024
	ds_read_b128 v[180:183], v175 offset:2048
	ds_read_b128 v[184:187], v175 offset:3072
	ds_read_b128 v[188:191], v171 offset:32768
	ds_read_b128 v[192:195], v171 offset:33792
	ds_read_b128 v[196:199], v171 offset:34816
	ds_read_b128 v[200:203], v171 offset:35840
	ds_read_b128 v[204:207], v171 offset:36864
	ds_read_b128 v[208:211], v171 offset:37888
	ds_read_b128 v[212:215], v171 offset:38912
	ds_read_b128 v[216:219], v171 offset:39936
	s_waitcnt vmcnt(8)
	s_waitcnt lgkmcnt(0)
	s_barrier
	s_setprio 1
	s_waitcnt lgkmcnt(0)
	v_mfma_f32_16x16x32_bf16 v[124:127], v[128:131], v[188:191], v[124:127]
	v_mfma_f32_16x16x32_bf16 v[120:123], v[136:139], v[188:191], v[120:123]
	v_mfma_f32_16x16x32_bf16 v[116:119], v[128:131], v[196:199], v[116:119]
	v_mfma_f32_16x16x32_bf16 v[112:115], v[136:139], v[196:199], v[112:115]
	v_mfma_f32_16x16x32_bf16 v[108:111], v[128:131], v[204:207], v[108:111]
	v_mfma_f32_16x16x32_bf16 v[104:107], v[136:139], v[204:207], v[104:107]
	v_mfma_f32_16x16x32_bf16 v[100:103], v[128:131], v[212:215], v[100:103]
	v_mfma_f32_16x16x32_bf16 v[96:99], v[136:139], v[212:215], v[96:99]
	v_mfma_f32_16x16x32_bf16 v[124:127], v[132:135], v[192:195], v[124:127]
	v_mfma_f32_16x16x32_bf16 v[120:123], v[140:143], v[192:195], v[120:123]
	v_mfma_f32_16x16x32_bf16 v[116:119], v[132:135], v[200:203], v[116:119]
	v_mfma_f32_16x16x32_bf16 v[112:115], v[140:143], v[200:203], v[112:115]
	v_mfma_f32_16x16x32_bf16 v[108:111], v[132:135], v[208:211], v[108:111]
	v_mfma_f32_16x16x32_bf16 v[104:107], v[140:143], v[208:211], v[104:107]
	v_mfma_f32_16x16x32_bf16 v[100:103], v[132:135], v[216:219], v[100:103]
	v_mfma_f32_16x16x32_bf16 v[96:99], v[140:143], v[216:219], v[96:99]
	s_setprio 0
	s_setprio 1
	v_mfma_f32_16x16x32_bf16 v[68:71], v[160:163], v[188:191], v[68:71]
	v_mfma_f32_16x16x32_bf16 v[64:67], v[180:183], v[188:191], v[64:67]
	v_mfma_f32_16x16x32_bf16 v[52:55], v[160:163], v[196:199], v[52:55]
	v_mfma_f32_16x16x32_bf16 v[48:51], v[180:183], v[196:199], v[48:51]
	v_mfma_f32_16x16x32_bf16 v[44:47], v[160:163], v[204:207], v[44:47]
	v_mfma_f32_16x16x32_bf16 v[40:43], v[180:183], v[204:207], v[40:43]
	v_mfma_f32_16x16x32_bf16 v[36:39], v[160:163], v[212:215], v[36:39]
	v_mfma_f32_16x16x32_bf16 v[32:35], v[180:183], v[212:215], v[32:35]
	v_mfma_f32_16x16x32_bf16 v[68:71], v[176:179], v[192:195], v[68:71]
	v_mfma_f32_16x16x32_bf16 v[64:67], v[184:187], v[192:195], v[64:67]
	v_mfma_f32_16x16x32_bf16 v[52:55], v[176:179], v[200:203], v[52:55]
	v_mfma_f32_16x16x32_bf16 v[48:51], v[184:187], v[200:203], v[48:51]
	v_mfma_f32_16x16x32_bf16 v[44:47], v[176:179], v[208:211], v[44:47]
	v_mfma_f32_16x16x32_bf16 v[40:43], v[184:187], v[208:211], v[40:43]
	v_mfma_f32_16x16x32_bf16 v[36:39], v[176:179], v[216:219], v[36:39]
	v_mfma_f32_16x16x32_bf16 v[32:35], v[184:187], v[216:219], v[32:35]
	s_setprio 0
	s_barrier
; #define PG8_STAGE(bufoff, gbase, voff) do { _Pragma("unroll") for (int _i = 0; _i < 2; ++_i) \
;         __builtin_amdgcn_global_load_lds((const unsigned*)((const char*)(gbase) + (voff)[_i]), (PG8_LAS unsigned*)(lds + (bufoff) + ldsw + _i * 8192), 16, 0, 0); } while (0)
; #define PG8_LDA(dst, b, h) do { _Pragma("unroll") for (int m = 0; m < 4; ++m) _Pragma("unroll") for (int k = 0; k < 2; ++k) dst[m][k] = *(const PG8_LAS bf16x8*)(lds + PG8_SA(b, h) + aoff + m * 2048 + k * 1024); } while (0)
; #define PG8_MMA(ai, bj, At, Bt) do { __builtin_amdgcn_s_setprio(1); _Pragma("unroll") for (int m = 0; m < 4; ++m) _Pragma("unroll") for (int n = 0; n < 2; ++n) _Pragma("unroll") for (int k = 0; k < 2; ++k) \
;         acc[ai][bj][m][n] = __builtin_amdgcn_mfma_f32_16x16x32_bf16(Bt[n][k], At[m][k], acc[ai][bj][m][n], 0, 0, 0); __builtin_amdgcn_s_setprio(0); } while (0)
; #define PG8_WAIT_V(n) asm volatile("s_waitcnt vmcnt(" #n ")" ::: "memory")
; #define PG8_WAIT_L(n) asm volatile("s_waitcnt lgkmcnt(" #n ")" ::: "memory")
; #define PG8_BAR __builtin_amdgcn_s_barrier()
; #define PG8_SCHED __builtin_amdgcn_sched_barrier(0)
; template <class Epi, class Sched, bool ALIGN_EPI = false, bool SP2 = false>
; __device__ __forceinline__ void gemm_phase(PG8_LAS unsigned char* lds, const Gemm g, const Sched& S, const Epi& E) {
;     ...
;             PG8_LDA(At, 1, 1); PG8_STAGE(PG8_SB(1, 0), b3, voffB); PG8_STAGE(PG8_SB(1, 1), b3 + hstepB, voffB); PG8_STAGE(PG8_SA(1, 0), a3, voffA);
;             PG8_WAIT_V(8); PG8_WAIT_L(0); PG8_BAR; PG8_MMA(1, 0, At, B0); PG8_MMA(1, 1, At, B1); PG8_BAR; PG8_SCHED;
;     ...
;         if constexpr (ALIGN_EPI) { if (wr == 0) PG8_BAR; }
	s_add_i32 s33, s33, s23
	v_lshl_add_u64 v[164:165], v[164:165], 0, s[6:7]
	s_mov_b32 m0, s33
	global_load_lds_dwordx4 v[164:165], off
	s_add_i32 m0, s33, 0x2000
	s_add_u32 s36, s40, 0xb0080
	v_lshl_add_u64 v[164:165], v[172:173], 0, s[6:7]
	s_addc_u32 s37, s41, 0
	s_add_i32 s33, s63, s23
	global_load_lds_dwordx4 v[164:165], off
	v_lshl_add_u64 v[164:165], s[36:37], 0, v[146:147]
	s_mov_b32 m0, s33
	s_nop 0
	global_load_lds_dwordx4 v[164:165], off
	v_lshl_add_u64 v[164:165], s[36:37], 0, v[150:151]
	s_add_i32 m0, s33, 0x2000
	s_nop 0
	global_load_lds_dwordx4 v[164:165], off
	v_lshl_add_u64 v[164:165], v[220:221], 0, s[6:7]
	s_mov_b32 m0, s46
	s_nop 0
	global_load_lds_dwordx4 v[164:165], off
	v_lshl_add_u64 v[164:165], v[222:223], 0, s[6:7]
	s_mov_b32 m0, s47
	s_nop 0
	global_load_lds_dwordx4 v[164:165], off
	ds_read_b128 v[188:191], v171 offset:49152
	ds_read_b128 v[192:195], v171 offset:50176
	ds_read_b128 v[196:199], v171 offset:51200
	ds_read_b128 v[200:203], v171 offset:52224
	ds_read_b128 v[204:207], v171 offset:53248
	ds_read_b128 v[208:211], v171 offset:54272
	ds_read_b128 v[212:215], v171 offset:55296
	ds_read_b128 v[216:219], v171 offset:56320
	s_waitcnt vmcnt(8)
	s_waitcnt lgkmcnt(0)
	s_barrier
	s_setprio 1
	s_waitcnt lgkmcnt(0)
	v_mfma_f32_16x16x32_bf16 v[92:95], v[128:131], v[188:191], v[92:95]
	v_mfma_f32_16x16x32_bf16 v[88:91], v[136:139], v[188:191], v[88:91]
	v_mfma_f32_16x16x32_bf16 v[84:87], v[128:131], v[196:199], v[84:87]
	v_mfma_f32_16x16x32_bf16 v[80:83], v[136:139], v[196:199], v[80:83]
	v_mfma_f32_16x16x32_bf16 v[76:79], v[128:131], v[204:207], v[76:79]
	v_mfma_f32_16x16x32_bf16 v[72:75], v[136:139], v[204:207], v[72:75]
	v_mfma_f32_16x16x32_bf16 v[60:63], v[128:131], v[212:215], v[60:63]
	v_mfma_f32_16x16x32_bf16 v[56:59], v[136:139], v[212:215], v[56:59]
	v_mfma_f32_16x16x32_bf16 v[92:95], v[132:135], v[192:195], v[92:95]
	v_mfma_f32_16x16x32_bf16 v[88:91], v[140:143], v[192:195], v[88:91]
	v_mfma_f32_16x16x32_bf16 v[84:87], v[132:135], v[200:203], v[84:87]
	v_mfma_f32_16x16x32_bf16 v[80:83], v[140:143], v[200:203], v[80:83]
	v_mfma_f32_16x16x32_bf16 v[76:79], v[132:135], v[208:211], v[76:79]
	v_mfma_f32_16x16x32_bf16 v[72:75], v[140:143], v[208:211], v[72:75]
	v_mfma_f32_16x16x32_bf16 v[60:63], v[132:135], v[216:219], v[60:63]
	v_mfma_f32_16x16x32_bf16 v[56:59], v[140:143], v[216:219], v[56:59]
	s_setprio 0
	s_setprio 1
	v_mfma_f32_16x16x32_bf16 v[28:31], v[160:163], v[188:191], v[28:31]
	v_mfma_f32_16x16x32_bf16 v[24:27], v[180:183], v[188:191], v[24:27]
	v_mfma_f32_16x16x32_bf16 v[20:23], v[160:163], v[196:199], v[20:23]
	v_mfma_f32_16x16x32_bf16 v[16:19], v[180:183], v[196:199], v[16:19]
	v_mfma_f32_16x16x32_bf16 v[12:15], v[160:163], v[204:207], v[12:15]
	v_mfma_f32_16x16x32_bf16 v[8:11], v[180:183], v[204:207], v[8:11]
	v_mfma_f32_16x16x32_bf16 v[4:7], v[160:163], v[212:215], v[4:7]
	v_mfma_f32_16x16x32_bf16 v[0:3], v[180:183], v[212:215], v[0:3]
	v_mfma_f32_16x16x32_bf16 v[28:31], v[176:179], v[192:195], v[28:31]
	v_mfma_f32_16x16x32_bf16 v[24:27], v[184:187], v[192:195], v[24:27]
	v_mfma_f32_16x16x32_bf16 v[20:23], v[176:179], v[200:203], v[20:23]
	v_mfma_f32_16x16x32_bf16 v[16:19], v[184:187], v[200:203], v[16:19]
	v_mfma_f32_16x16x32_bf16 v[12:15], v[176:179], v[208:211], v[12:15]
	v_mfma_f32_16x16x32_bf16 v[8:11], v[184:187], v[208:211], v[8:11]
	v_mfma_f32_16x16x32_bf16 v[4:7], v[176:179], v[216:219], v[4:7]
	v_mfma_f32_16x16x32_bf16 v[0:3], v[184:187], v[216:219], v[0:3]
	s_setprio 0
	s_barrier
	s_add_i32 s62, s62, 2
	s_add_u32 s60, s60, 0x100
	s_addc_u32 s61, s61, 0
	s_cmp_gt_u32 s62, 41
	s_mov_b64 s[36:37], s[38:39]
	s_cbranch_scc0 .LBB0_685
	s_and_b64 vcc, exec, s[8:9]
	s_cbranch_vccz .LBB0_688
	s_barrier
